# PN phase: hand-written residual epilogue (register ring, packed f32, two compact row-sum stores) with the first two residual rows fetched during the last K trip
# speedup vs baseline: 1.0059x; 1.0024x over previous
.LBB0_603:
	ds_read_b128 v[128:131], v181
	ds_read_b128 v[132:135], v181 offset:1024
	ds_read_b128 v[136:139], v181 offset:2048
	ds_read_b128 v[140:143], v181 offset:3072
	ds_read_b128 v[144:147], v182
	ds_read_b128 v[148:151], v182 offset:1024
	ds_read_b128 v[168:171], v182 offset:2048
	ds_read_b128 v[172:175], v182 offset:3072
	s_add_u32 s40, s38, 0xfffc0080
	s_addc_u32 s41, s39, -1
	s_cmp_eq_u32 s56, 12
	s_cselect_b32 s43, s35, s41
	s_cselect_b32 s42, s34, s40
	s_cselect_b32 s41, s37, s31
	s_cselect_b32 s40, s36, s29
	v_lshl_add_u64 v[176:177], s[38:39], 0, v[160:161]
	s_add_i32 m0, s17, 0xc000
	ds_read_b128 v[186:189], v183
	ds_read_b128 v[190:193], v183 offset:1024
	ds_read_b128 v[194:197], v183 offset:2048
	ds_read_b128 v[202:205], v183 offset:3072
	ds_read_b128 v[206:209], v183 offset:4096
	ds_read_b128 v[210:213], v183 offset:5120
	ds_read_b128 v[214:217], v183 offset:6144
	ds_read_b128 v[218:221], v183 offset:7168
	global_load_lds_dwordx4 v[176:177], off
	v_lshl_add_u64 v[176:177], s[38:39], 0, v[162:163]
	s_add_i32 m0, s17, 0xe000
	s_nop 0
	global_load_lds_dwordx4 v[176:177], off
	s_waitcnt vmcnt(8)
	s_waitcnt lgkmcnt(0)
	s_barrier
	s_setprio 1
	s_waitcnt lgkmcnt(0)
	v_mfma_f32_16x16x32_bf16 v[124:127], v[128:131], v[186:189], v[124:127]
	v_mfma_f32_16x16x32_bf16 v[120:123], v[136:139], v[186:189], v[120:123]
	v_mfma_f32_16x16x32_bf16 v[108:111], v[128:131], v[194:197], v[108:111]
	v_mfma_f32_16x16x32_bf16 v[104:107], v[136:139], v[194:197], v[104:107]
	v_mfma_f32_16x16x32_bf16 v[92:95], v[128:131], v[206:209], v[92:95]
	v_mfma_f32_16x16x32_bf16 v[88:91], v[136:139], v[206:209], v[88:91]
	v_mfma_f32_16x16x32_bf16 v[76:79], v[128:131], v[214:217], v[76:79]
	v_mfma_f32_16x16x32_bf16 v[72:75], v[136:139], v[214:217], v[72:75]
	v_mfma_f32_16x16x32_bf16 v[124:127], v[132:135], v[190:193], v[124:127]
	v_mfma_f32_16x16x32_bf16 v[120:123], v[140:143], v[190:193], v[120:123]
	v_mfma_f32_16x16x32_bf16 v[108:111], v[132:135], v[202:205], v[108:111]
	v_mfma_f32_16x16x32_bf16 v[104:107], v[140:143], v[202:205], v[104:107]
	v_mfma_f32_16x16x32_bf16 v[92:95], v[132:135], v[210:213], v[92:95]
	v_mfma_f32_16x16x32_bf16 v[88:91], v[140:143], v[210:213], v[88:91]
	v_mfma_f32_16x16x32_bf16 v[76:79], v[132:135], v[218:221], v[76:79]
	v_mfma_f32_16x16x32_bf16 v[72:75], v[140:143], v[218:221], v[72:75]
	s_setprio 0
	s_setprio 1
	v_mfma_f32_16x16x32_bf16 v[116:119], v[144:147], v[186:189], v[116:119]
	v_mfma_f32_16x16x32_bf16 v[112:115], v[168:171], v[186:189], v[112:115]
	v_mfma_f32_16x16x32_bf16 v[100:103], v[144:147], v[194:197], v[100:103]
	v_mfma_f32_16x16x32_bf16 v[96:99], v[168:171], v[194:197], v[96:99]
	v_mfma_f32_16x16x32_bf16 v[84:87], v[144:147], v[206:209], v[84:87]
	v_mfma_f32_16x16x32_bf16 v[80:83], v[168:171], v[206:209], v[80:83]
	v_mfma_f32_16x16x32_bf16 v[68:71], v[144:147], v[214:217], v[68:71]
	v_mfma_f32_16x16x32_bf16 v[64:67], v[168:171], v[214:217], v[64:67]
	v_mfma_f32_16x16x32_bf16 v[116:119], v[148:151], v[190:193], v[116:119]
	v_mfma_f32_16x16x32_bf16 v[112:115], v[172:175], v[190:193], v[112:115]
	v_mfma_f32_16x16x32_bf16 v[100:103], v[148:151], v[202:205], v[100:103]
	v_mfma_f32_16x16x32_bf16 v[96:99], v[172:175], v[202:205], v[96:99]
	v_mfma_f32_16x16x32_bf16 v[84:87], v[148:151], v[210:213], v[84:87]
	v_mfma_f32_16x16x32_bf16 v[80:83], v[172:175], v[210:213], v[80:83]
	v_mfma_f32_16x16x32_bf16 v[68:71], v[148:151], v[218:221], v[68:71]
	v_mfma_f32_16x16x32_bf16 v[64:67], v[172:175], v[218:221], v[64:67]
	s_setprio 0
	s_barrier
	s_add_i32 s57, s33, s9
	v_lshl_add_u64 v[176:177], s[40:41], 0, v[154:155]
	s_mov_b32 m0, s57
	ds_read_b128 v[186:189], v183 offset:16384
	ds_read_b128 v[190:193], v183 offset:17408
	ds_read_b128 v[194:197], v183 offset:18432
	ds_read_b128 v[202:205], v183 offset:19456
	ds_read_b128 v[206:209], v183 offset:20480
	ds_read_b128 v[210:213], v183 offset:21504
	ds_read_b128 v[214:217], v183 offset:22528
	ds_read_b128 v[218:221], v183 offset:23552
	global_load_lds_dwordx4 v[176:177], off
	s_add_i32 m0, s57, 0x2000
	s_add_u32 s58, s40, 0x40000
	v_lshl_add_u64 v[198:199], s[40:41], 0, v[158:159]
	s_addc_u32 s59, s41, 0
	s_add_i32 s57, s53, s9
	global_load_lds_dwordx4 v[198:199], off
	v_lshl_add_u64 v[222:223], s[58:59], 0, v[154:155]
	s_mov_b32 m0, s57
	v_lshl_add_u64 v[224:225], s[42:43], 0, v[156:157]
	global_load_lds_dwordx4 v[222:223], off
	v_lshl_add_u64 v[222:223], s[58:59], 0, v[158:159]
	s_add_i32 m0, s57, 0x2000
	s_nop 0
	global_load_lds_dwordx4 v[222:223], off
	v_lshl_add_u64 v[222:223], s[42:43], 0, v[152:153]
	s_mov_b32 m0, s17
	s_nop 0
	global_load_lds_dwordx4 v[222:223], off
	s_mov_b32 m0, s45
	s_nop 0
	global_load_lds_dwordx4 v[224:225], off
	s_waitcnt vmcnt(8)
	s_waitcnt lgkmcnt(0)
	s_barrier
	s_setprio 1
	s_waitcnt lgkmcnt(0)
	v_mfma_f32_16x16x32_bf16 v[60:63], v[128:131], v[186:189], v[60:63]
	v_mfma_f32_16x16x32_bf16 v[56:59], v[136:139], v[186:189], v[56:59]
	v_mfma_f32_16x16x32_bf16 v[44:47], v[128:131], v[194:197], v[44:47]
	v_mfma_f32_16x16x32_bf16 v[40:43], v[136:139], v[194:197], v[40:43]
	v_mfma_f32_16x16x32_bf16 v[28:31], v[128:131], v[206:209], v[28:31]
	v_mfma_f32_16x16x32_bf16 v[24:27], v[136:139], v[206:209], v[24:27]
	v_mfma_f32_16x16x32_bf16 v[12:15], v[128:131], v[214:217], v[12:15]
	v_mfma_f32_16x16x32_bf16 v[8:11], v[136:139], v[214:217], v[8:11]
	v_mfma_f32_16x16x32_bf16 v[60:63], v[132:135], v[190:193], v[60:63]
	v_mfma_f32_16x16x32_bf16 v[56:59], v[140:143], v[190:193], v[56:59]
	v_mfma_f32_16x16x32_bf16 v[44:47], v[132:135], v[202:205], v[44:47]
	v_mfma_f32_16x16x32_bf16 v[40:43], v[140:143], v[202:205], v[40:43]
	v_mfma_f32_16x16x32_bf16 v[28:31], v[132:135], v[210:213], v[28:31]
	v_mfma_f32_16x16x32_bf16 v[24:27], v[140:143], v[210:213], v[24:27]
	v_mfma_f32_16x16x32_bf16 v[12:15], v[132:135], v[218:221], v[12:15]
	v_mfma_f32_16x16x32_bf16 v[8:11], v[140:143], v[218:221], v[8:11]
	s_setprio 0
	s_setprio 1
	v_mfma_f32_16x16x32_bf16 v[52:55], v[144:147], v[186:189], v[52:55]
	v_mfma_f32_16x16x32_bf16 v[48:51], v[168:171], v[186:189], v[48:51]
	v_mfma_f32_16x16x32_bf16 v[36:39], v[144:147], v[194:197], v[36:39]
	v_mfma_f32_16x16x32_bf16 v[32:35], v[168:171], v[194:197], v[32:35]
	v_mfma_f32_16x16x32_bf16 v[20:23], v[144:147], v[206:209], v[20:23]
	v_mfma_f32_16x16x32_bf16 v[16:19], v[168:171], v[206:209], v[16:19]
	v_mfma_f32_16x16x32_bf16 v[4:7], v[144:147], v[214:217], v[4:7]
	v_mfma_f32_16x16x32_bf16 v[0:3], v[168:171], v[214:217], v[0:3]
	v_mfma_f32_16x16x32_bf16 v[52:55], v[148:151], v[190:193], v[52:55]
	v_mfma_f32_16x16x32_bf16 v[48:51], v[172:175], v[190:193], v[48:51]
	v_mfma_f32_16x16x32_bf16 v[36:39], v[148:151], v[202:205], v[36:39]
	v_mfma_f32_16x16x32_bf16 v[32:35], v[172:175], v[202:205], v[32:35]
	v_mfma_f32_16x16x32_bf16 v[20:23], v[148:151], v[210:213], v[20:23]
	v_mfma_f32_16x16x32_bf16 v[16:19], v[172:175], v[210:213], v[16:19]
	v_mfma_f32_16x16x32_bf16 v[4:7], v[148:151], v[218:221], v[4:7]
	v_mfma_f32_16x16x32_bf16 v[0:3], v[172:175], v[218:221], v[0:3]
	s_setprio 0
	s_barrier
	s_add_i32 s57, 0, 0x18000
	s_add_i32 s58, 0, 0x1c000
	v_add_u32_e32 v140, s57, v179
	v_add_u32_e32 v172, s58, v179
	ds_read_b128 v[128:131], v140
	ds_read_b128 v[132:135], v140 offset:1024
	ds_read_b128 v[136:139], v140 offset:2048
	ds_read_b128 v[140:143], v140 offset:3072
	ds_read_b128 v[144:147], v172
	ds_read_b128 v[148:151], v172 offset:1024
	ds_read_b128 v[168:171], v172 offset:2048
	ds_read_b128 v[172:175], v172 offset:3072
	s_add_u32 s42, s42, 0x40000
	s_addc_u32 s43, s43, 0
	s_mov_b32 m0, s46
	v_lshl_add_u64 v[226:227], s[42:43], 0, v[152:153]
	ds_read_b128 v[186:189], v183 offset:32768
	ds_read_b128 v[190:193], v183 offset:33792
	ds_read_b128 v[194:197], v183 offset:34816
	ds_read_b128 v[202:205], v183 offset:35840
	ds_read_b128 v[206:209], v183 offset:36864
	ds_read_b128 v[210:213], v183 offset:37888
	ds_read_b128 v[214:217], v183 offset:38912
	ds_read_b128 v[218:221], v183 offset:39936
	global_load_lds_dwordx4 v[226:227], off
	v_lshl_add_u64 v[226:227], s[42:43], 0, v[156:157]
	s_mov_b32 m0, s47
	s_nop 0
	global_load_lds_dwordx4 v[226:227], off
	s_waitcnt vmcnt(8)
	s_waitcnt lgkmcnt(0)
	s_barrier
	s_setprio 1
	s_waitcnt lgkmcnt(0)
	v_mfma_f32_16x16x32_bf16 v[124:127], v[128:131], v[186:189], v[124:127]
	v_mfma_f32_16x16x32_bf16 v[120:123], v[136:139], v[186:189], v[120:123]
	v_mfma_f32_16x16x32_bf16 v[108:111], v[128:131], v[194:197], v[108:111]
	v_mfma_f32_16x16x32_bf16 v[104:107], v[136:139], v[194:197], v[104:107]
	v_mfma_f32_16x16x32_bf16 v[92:95], v[128:131], v[206:209], v[92:95]
	v_mfma_f32_16x16x32_bf16 v[88:91], v[136:139], v[206:209], v[88:91]
	v_mfma_f32_16x16x32_bf16 v[76:79], v[128:131], v[214:217], v[76:79]
	v_mfma_f32_16x16x32_bf16 v[72:75], v[136:139], v[214:217], v[72:75]
	v_mfma_f32_16x16x32_bf16 v[124:127], v[132:135], v[190:193], v[124:127]
	v_mfma_f32_16x16x32_bf16 v[120:123], v[140:143], v[190:193], v[120:123]
	v_mfma_f32_16x16x32_bf16 v[108:111], v[132:135], v[202:205], v[108:111]
	v_mfma_f32_16x16x32_bf16 v[104:107], v[140:143], v[202:205], v[104:107]
	v_mfma_f32_16x16x32_bf16 v[92:95], v[132:135], v[210:213], v[92:95]
	v_mfma_f32_16x16x32_bf16 v[88:91], v[140:143], v[210:213], v[88:91]
	v_mfma_f32_16x16x32_bf16 v[76:79], v[132:135], v[218:221], v[76:79]
	v_mfma_f32_16x16x32_bf16 v[72:75], v[140:143], v[218:221], v[72:75]
	s_setprio 0
	s_setprio 1
	v_mfma_f32_16x16x32_bf16 v[116:119], v[144:147], v[186:189], v[116:119]
	v_mfma_f32_16x16x32_bf16 v[112:115], v[168:171], v[186:189], v[112:115]
	v_mfma_f32_16x16x32_bf16 v[100:103], v[144:147], v[194:197], v[100:103]
	v_mfma_f32_16x16x32_bf16 v[96:99], v[168:171], v[194:197], v[96:99]
	v_mfma_f32_16x16x32_bf16 v[84:87], v[144:147], v[206:209], v[84:87]
	v_mfma_f32_16x16x32_bf16 v[80:83], v[168:171], v[206:209], v[80:83]
	v_mfma_f32_16x16x32_bf16 v[68:71], v[144:147], v[214:217], v[68:71]
	v_mfma_f32_16x16x32_bf16 v[64:67], v[168:171], v[214:217], v[64:67]
	v_mfma_f32_16x16x32_bf16 v[116:119], v[148:151], v[190:193], v[116:119]
	v_mfma_f32_16x16x32_bf16 v[112:115], v[172:175], v[190:193], v[112:115]
	v_mfma_f32_16x16x32_bf16 v[100:103], v[148:151], v[202:205], v[100:103]
	v_mfma_f32_16x16x32_bf16 v[96:99], v[172:175], v[202:205], v[96:99]
	v_mfma_f32_16x16x32_bf16 v[84:87], v[148:151], v[210:213], v[84:87]
	v_mfma_f32_16x16x32_bf16 v[80:83], v[172:175], v[210:213], v[80:83]
	v_mfma_f32_16x16x32_bf16 v[68:71], v[148:151], v[218:221], v[68:71]
	v_mfma_f32_16x16x32_bf16 v[64:67], v[172:175], v[218:221], v[64:67]
	s_setprio 0
	s_barrier
	s_add_i32 s42, s57, s9
	v_lshl_add_u64 v[176:177], v[176:177], 0, s[20:21]
	s_mov_b32 m0, s42
	ds_read_b128 v[186:189], v183 offset:49152
	ds_read_b128 v[190:193], v183 offset:50176
	ds_read_b128 v[194:197], v183 offset:51200
	ds_read_b128 v[202:205], v183 offset:52224
	ds_read_b128 v[206:209], v183 offset:53248
	ds_read_b128 v[210:213], v183 offset:54272
	ds_read_b128 v[214:217], v183 offset:55296
	ds_read_b128 v[218:221], v183 offset:56320
	global_load_lds_dwordx4 v[176:177], off
	s_add_i32 m0, s42, 0x2000
	s_add_u32 s40, s40, 0x40080
	v_lshl_add_u64 v[176:177], v[198:199], 0, s[20:21]
	s_addc_u32 s41, s41, 0
	s_add_i32 s42, s58, s9
	global_load_lds_dwordx4 v[176:177], off
	v_lshl_add_u64 v[176:177], s[40:41], 0, v[154:155]
	s_mov_b32 m0, s42
	s_nop 0
	global_load_lds_dwordx4 v[176:177], off
	v_lshl_add_u64 v[176:177], s[40:41], 0, v[158:159]
	s_add_i32 m0, s42, 0x2000
	s_nop 0
	global_load_lds_dwordx4 v[176:177], off
	v_lshl_add_u64 v[176:177], v[222:223], 0, s[20:21]
	s_mov_b32 m0, s51
	s_nop 0
	global_load_lds_dwordx4 v[176:177], off
	v_lshl_add_u64 v[176:177], v[224:225], 0, s[20:21]
	s_mov_b32 m0, s52
	s_nop 0
	global_load_lds_dwordx4 v[176:177], off
	s_waitcnt vmcnt(8)
	s_waitcnt lgkmcnt(0)
	s_barrier
	s_setprio 1
	s_waitcnt lgkmcnt(0)
	v_mfma_f32_16x16x32_bf16 v[60:63], v[128:131], v[186:189], v[60:63]
	v_mfma_f32_16x16x32_bf16 v[56:59], v[136:139], v[186:189], v[56:59]
	v_mfma_f32_16x16x32_bf16 v[44:47], v[128:131], v[194:197], v[44:47]
	v_mfma_f32_16x16x32_bf16 v[40:43], v[136:139], v[194:197], v[40:43]
	v_mfma_f32_16x16x32_bf16 v[28:31], v[128:131], v[206:209], v[28:31]
	v_mfma_f32_16x16x32_bf16 v[24:27], v[136:139], v[206:209], v[24:27]
	v_mfma_f32_16x16x32_bf16 v[12:15], v[128:131], v[214:217], v[12:15]
	v_mfma_f32_16x16x32_bf16 v[8:11], v[136:139], v[214:217], v[8:11]
	v_mfma_f32_16x16x32_bf16 v[60:63], v[132:135], v[190:193], v[60:63]
	v_mfma_f32_16x16x32_bf16 v[56:59], v[140:143], v[190:193], v[56:59]
	v_mfma_f32_16x16x32_bf16 v[44:47], v[132:135], v[202:205], v[44:47]
	v_mfma_f32_16x16x32_bf16 v[40:43], v[140:143], v[202:205], v[40:43]
	v_mfma_f32_16x16x32_bf16 v[28:31], v[132:135], v[210:213], v[28:31]
	v_mfma_f32_16x16x32_bf16 v[24:27], v[140:143], v[210:213], v[24:27]
	v_mfma_f32_16x16x32_bf16 v[12:15], v[132:135], v[218:221], v[12:15]
	v_mfma_f32_16x16x32_bf16 v[8:11], v[140:143], v[218:221], v[8:11]
	s_setprio 0
	s_setprio 1
	v_mfma_f32_16x16x32_bf16 v[52:55], v[144:147], v[186:189], v[52:55]
	v_mfma_f32_16x16x32_bf16 v[48:51], v[168:171], v[186:189], v[48:51]
	v_mfma_f32_16x16x32_bf16 v[36:39], v[144:147], v[194:197], v[36:39]
	v_mfma_f32_16x16x32_bf16 v[32:35], v[168:171], v[194:197], v[32:35]
	v_mfma_f32_16x16x32_bf16 v[20:23], v[144:147], v[206:209], v[20:23]
	v_mfma_f32_16x16x32_bf16 v[16:19], v[168:171], v[206:209], v[16:19]
	v_mfma_f32_16x16x32_bf16 v[4:7], v[144:147], v[214:217], v[4:7]
	v_mfma_f32_16x16x32_bf16 v[0:3], v[168:171], v[214:217], v[0:3]
	v_mfma_f32_16x16x32_bf16 v[52:55], v[148:151], v[190:193], v[52:55]
	v_mfma_f32_16x16x32_bf16 v[48:51], v[172:175], v[190:193], v[48:51]
	v_mfma_f32_16x16x32_bf16 v[36:39], v[148:151], v[202:205], v[36:39]
	v_mfma_f32_16x16x32_bf16 v[32:35], v[172:175], v[202:205], v[32:35]
	v_mfma_f32_16x16x32_bf16 v[20:23], v[148:151], v[210:213], v[20:23]
	v_mfma_f32_16x16x32_bf16 v[16:19], v[172:175], v[210:213], v[16:19]
	v_mfma_f32_16x16x32_bf16 v[4:7], v[148:151], v[218:221], v[4:7]
	v_mfma_f32_16x16x32_bf16 v[0:3], v[172:175], v[218:221], v[0:3]
	s_setprio 0
	s_barrier
	s_add_i32 s56, s56, 2
	s_add_u32 s38, s38, 0x100
	s_addc_u32 s39, s39, 0
	s_add_u32 s29, s29, 0x100
	s_addc_u32 s31, s31, 0
	s_cmp_gt_u32 s56, 11
	s_cbranch_scc0 .LBB0_603
	v_lshl_add_u32 v244, s10, 8, v178
	v_lshl_or_b32 v245, s55, 8, v180
	v_lshlrev_b32_e32 v244, 11, v244
	v_lshl_add_u32 v244, v245, 1, v244
	v_add_u32_e32 v245, 0x8000, v244
	global_load_dwordx4 v[228:231], v244, s[74:75]
	global_load_dwordx4 v[232:235], v244, s[74:75] offset:256
	global_load_dwordx4 v[236:239], v245, s[74:75]
	global_load_dwordx4 v[240:243], v245, s[74:75] offset:256
	ds_read_b128 v[128:131], v181
	ds_read_b128 v[132:135], v181 offset:1024
	ds_read_b128 v[136:139], v181 offset:2048
	ds_read_b128 v[140:143], v181 offset:3072
	ds_read_b128 v[144:147], v182
	ds_read_b128 v[148:151], v182 offset:1024
	ds_read_b128 v[168:171], v182 offset:2048
	ds_read_b128 v[172:175], v182 offset:3072
	s_add_u32 s40, s38, 0xfffc0080
	s_addc_u32 s41, s39, -1
	s_cmp_eq_u32 s56, 12
	s_cselect_b32 s43, s35, s41
	s_cselect_b32 s42, s34, s40
	s_cselect_b32 s41, s37, s31
	s_cselect_b32 s40, s36, s29
	v_lshl_add_u64 v[176:177], s[38:39], 0, v[160:161]
	s_add_i32 m0, s17, 0xc000
	ds_read_b128 v[186:189], v183
	ds_read_b128 v[190:193], v183 offset:1024
	ds_read_b128 v[194:197], v183 offset:2048
	ds_read_b128 v[202:205], v183 offset:3072
	ds_read_b128 v[206:209], v183 offset:4096
	ds_read_b128 v[210:213], v183 offset:5120
	ds_read_b128 v[214:217], v183 offset:6144
	ds_read_b128 v[218:221], v183 offset:7168
	global_load_lds_dwordx4 v[176:177], off
	v_lshl_add_u64 v[176:177], s[38:39], 0, v[162:163]
	s_add_i32 m0, s17, 0xe000
	s_nop 0
	global_load_lds_dwordx4 v[176:177], off
	s_waitcnt vmcnt(12)
	s_waitcnt lgkmcnt(0)
	s_barrier
	s_setprio 1
	s_waitcnt lgkmcnt(0)
	v_mfma_f32_16x16x32_bf16 v[124:127], v[128:131], v[186:189], v[124:127]
	v_mfma_f32_16x16x32_bf16 v[120:123], v[136:139], v[186:189], v[120:123]
	v_mfma_f32_16x16x32_bf16 v[108:111], v[128:131], v[194:197], v[108:111]
	v_mfma_f32_16x16x32_bf16 v[104:107], v[136:139], v[194:197], v[104:107]
	v_mfma_f32_16x16x32_bf16 v[92:95], v[128:131], v[206:209], v[92:95]
	v_mfma_f32_16x16x32_bf16 v[88:91], v[136:139], v[206:209], v[88:91]
	v_mfma_f32_16x16x32_bf16 v[76:79], v[128:131], v[214:217], v[76:79]
	v_mfma_f32_16x16x32_bf16 v[72:75], v[136:139], v[214:217], v[72:75]
	v_mfma_f32_16x16x32_bf16 v[124:127], v[132:135], v[190:193], v[124:127]
	v_mfma_f32_16x16x32_bf16 v[120:123], v[140:143], v[190:193], v[120:123]
	v_mfma_f32_16x16x32_bf16 v[108:111], v[132:135], v[202:205], v[108:111]
	v_mfma_f32_16x16x32_bf16 v[104:107], v[140:143], v[202:205], v[104:107]
	v_mfma_f32_16x16x32_bf16 v[92:95], v[132:135], v[210:213], v[92:95]
	v_mfma_f32_16x16x32_bf16 v[88:91], v[140:143], v[210:213], v[88:91]
	v_mfma_f32_16x16x32_bf16 v[76:79], v[132:135], v[218:221], v[76:79]
	v_mfma_f32_16x16x32_bf16 v[72:75], v[140:143], v[218:221], v[72:75]
	s_setprio 0
	s_setprio 1
	v_mfma_f32_16x16x32_bf16 v[116:119], v[144:147], v[186:189], v[116:119]
	v_mfma_f32_16x16x32_bf16 v[112:115], v[168:171], v[186:189], v[112:115]
	v_mfma_f32_16x16x32_bf16 v[100:103], v[144:147], v[194:197], v[100:103]
	v_mfma_f32_16x16x32_bf16 v[96:99], v[168:171], v[194:197], v[96:99]
	v_mfma_f32_16x16x32_bf16 v[84:87], v[144:147], v[206:209], v[84:87]
	v_mfma_f32_16x16x32_bf16 v[80:83], v[168:171], v[206:209], v[80:83]
	v_mfma_f32_16x16x32_bf16 v[68:71], v[144:147], v[214:217], v[68:71]
	v_mfma_f32_16x16x32_bf16 v[64:67], v[168:171], v[214:217], v[64:67]
	v_mfma_f32_16x16x32_bf16 v[116:119], v[148:151], v[190:193], v[116:119]
	v_mfma_f32_16x16x32_bf16 v[112:115], v[172:175], v[190:193], v[112:115]
	v_mfma_f32_16x16x32_bf16 v[100:103], v[148:151], v[202:205], v[100:103]
	v_mfma_f32_16x16x32_bf16 v[96:99], v[172:175], v[202:205], v[96:99]
	v_mfma_f32_16x16x32_bf16 v[84:87], v[148:151], v[210:213], v[84:87]
	v_mfma_f32_16x16x32_bf16 v[80:83], v[172:175], v[210:213], v[80:83]
	v_mfma_f32_16x16x32_bf16 v[68:71], v[148:151], v[218:221], v[68:71]
	v_mfma_f32_16x16x32_bf16 v[64:67], v[172:175], v[218:221], v[64:67]
	s_setprio 0
	s_barrier
	s_add_i32 s57, s33, s9
	v_lshl_add_u64 v[176:177], s[40:41], 0, v[154:155]
	s_mov_b32 m0, s57
	ds_read_b128 v[186:189], v183 offset:16384
	ds_read_b128 v[190:193], v183 offset:17408
	ds_read_b128 v[194:197], v183 offset:18432
	ds_read_b128 v[202:205], v183 offset:19456
	ds_read_b128 v[206:209], v183 offset:20480
	ds_read_b128 v[210:213], v183 offset:21504
	ds_read_b128 v[214:217], v183 offset:22528
	ds_read_b128 v[218:221], v183 offset:23552
	global_load_lds_dwordx4 v[176:177], off
	s_add_i32 m0, s57, 0x2000
	s_add_u32 s58, s40, 0x40000
	v_lshl_add_u64 v[198:199], s[40:41], 0, v[158:159]
	s_addc_u32 s59, s41, 0
	s_add_i32 s57, s53, s9
	global_load_lds_dwordx4 v[198:199], off
	v_lshl_add_u64 v[222:223], s[58:59], 0, v[154:155]
	s_mov_b32 m0, s57
	v_lshl_add_u64 v[224:225], s[42:43], 0, v[156:157]
	global_load_lds_dwordx4 v[222:223], off
	v_lshl_add_u64 v[222:223], s[58:59], 0, v[158:159]
	s_add_i32 m0, s57, 0x2000
	s_nop 0
	global_load_lds_dwordx4 v[222:223], off
	v_lshl_add_u64 v[222:223], s[42:43], 0, v[152:153]
	s_mov_b32 m0, s17
	s_nop 0
	global_load_lds_dwordx4 v[222:223], off
	s_mov_b32 m0, s45
	s_nop 0
	global_load_lds_dwordx4 v[224:225], off
	s_waitcnt vmcnt(12)
	s_waitcnt lgkmcnt(0)
	s_barrier
	s_setprio 1
	s_waitcnt lgkmcnt(0)
	v_mfma_f32_16x16x32_bf16 v[60:63], v[128:131], v[186:189], v[60:63]
	v_mfma_f32_16x16x32_bf16 v[56:59], v[136:139], v[186:189], v[56:59]
	v_mfma_f32_16x16x32_bf16 v[44:47], v[128:131], v[194:197], v[44:47]
	v_mfma_f32_16x16x32_bf16 v[40:43], v[136:139], v[194:197], v[40:43]
	v_mfma_f32_16x16x32_bf16 v[28:31], v[128:131], v[206:209], v[28:31]
	v_mfma_f32_16x16x32_bf16 v[24:27], v[136:139], v[206:209], v[24:27]
	v_mfma_f32_16x16x32_bf16 v[12:15], v[128:131], v[214:217], v[12:15]
	v_mfma_f32_16x16x32_bf16 v[8:11], v[136:139], v[214:217], v[8:11]
	v_mfma_f32_16x16x32_bf16 v[60:63], v[132:135], v[190:193], v[60:63]
	v_mfma_f32_16x16x32_bf16 v[56:59], v[140:143], v[190:193], v[56:59]
	v_mfma_f32_16x16x32_bf16 v[44:47], v[132:135], v[202:205], v[44:47]
	v_mfma_f32_16x16x32_bf16 v[40:43], v[140:143], v[202:205], v[40:43]
	v_mfma_f32_16x16x32_bf16 v[28:31], v[132:135], v[210:213], v[28:31]
	v_mfma_f32_16x16x32_bf16 v[24:27], v[140:143], v[210:213], v[24:27]
	v_mfma_f32_16x16x32_bf16 v[12:15], v[132:135], v[218:221], v[12:15]
	v_mfma_f32_16x16x32_bf16 v[8:11], v[140:143], v[218:221], v[8:11]
	s_setprio 0
	s_setprio 1
	v_mfma_f32_16x16x32_bf16 v[52:55], v[144:147], v[186:189], v[52:55]
	v_mfma_f32_16x16x32_bf16 v[48:51], v[168:171], v[186:189], v[48:51]
	v_mfma_f32_16x16x32_bf16 v[36:39], v[144:147], v[194:197], v[36:39]
	v_mfma_f32_16x16x32_bf16 v[32:35], v[168:171], v[194:197], v[32:35]
	v_mfma_f32_16x16x32_bf16 v[20:23], v[144:147], v[206:209], v[20:23]
	v_mfma_f32_16x16x32_bf16 v[16:19], v[168:171], v[206:209], v[16:19]
	v_mfma_f32_16x16x32_bf16 v[4:7], v[144:147], v[214:217], v[4:7]
	v_mfma_f32_16x16x32_bf16 v[0:3], v[168:171], v[214:217], v[0:3]
	v_mfma_f32_16x16x32_bf16 v[52:55], v[148:151], v[190:193], v[52:55]
	v_mfma_f32_16x16x32_bf16 v[48:51], v[172:175], v[190:193], v[48:51]
	v_mfma_f32_16x16x32_bf16 v[36:39], v[148:151], v[202:205], v[36:39]
	v_mfma_f32_16x16x32_bf16 v[32:35], v[172:175], v[202:205], v[32:35]
	v_mfma_f32_16x16x32_bf16 v[20:23], v[148:151], v[210:213], v[20:23]
	v_mfma_f32_16x16x32_bf16 v[16:19], v[172:175], v[210:213], v[16:19]
	v_mfma_f32_16x16x32_bf16 v[4:7], v[148:151], v[218:221], v[4:7]
	v_mfma_f32_16x16x32_bf16 v[0:3], v[172:175], v[218:221], v[0:3]
	s_setprio 0
	s_barrier
	s_add_i32 s57, 0, 0x18000
	s_add_i32 s58, 0, 0x1c000
	v_add_u32_e32 v140, s57, v179
	v_add_u32_e32 v172, s58, v179
	ds_read_b128 v[128:131], v140
	ds_read_b128 v[132:135], v140 offset:1024
	ds_read_b128 v[136:139], v140 offset:2048
	ds_read_b128 v[140:143], v140 offset:3072
	ds_read_b128 v[144:147], v172
	ds_read_b128 v[148:151], v172 offset:1024
	ds_read_b128 v[168:171], v172 offset:2048
	ds_read_b128 v[172:175], v172 offset:3072
	s_add_u32 s42, s42, 0x40000
	s_addc_u32 s43, s43, 0
	s_mov_b32 m0, s46
	v_lshl_add_u64 v[226:227], s[42:43], 0, v[152:153]
	ds_read_b128 v[186:189], v183 offset:32768
	ds_read_b128 v[190:193], v183 offset:33792
	ds_read_b128 v[194:197], v183 offset:34816
	ds_read_b128 v[202:205], v183 offset:35840
	ds_read_b128 v[206:209], v183 offset:36864
	ds_read_b128 v[210:213], v183 offset:37888
	ds_read_b128 v[214:217], v183 offset:38912
	ds_read_b128 v[218:221], v183 offset:39936
	global_load_lds_dwordx4 v[226:227], off
	v_lshl_add_u64 v[226:227], s[42:43], 0, v[156:157]
	s_mov_b32 m0, s47
	s_nop 0
	global_load_lds_dwordx4 v[226:227], off
	s_waitcnt vmcnt(12)
	s_waitcnt lgkmcnt(0)
	s_barrier
	s_setprio 1
	s_waitcnt lgkmcnt(0)
	v_mfma_f32_16x16x32_bf16 v[124:127], v[128:131], v[186:189], v[124:127]
	v_mfma_f32_16x16x32_bf16 v[120:123], v[136:139], v[186:189], v[120:123]
	v_mfma_f32_16x16x32_bf16 v[108:111], v[128:131], v[194:197], v[108:111]
	v_mfma_f32_16x16x32_bf16 v[104:107], v[136:139], v[194:197], v[104:107]
	v_mfma_f32_16x16x32_bf16 v[92:95], v[128:131], v[206:209], v[92:95]
	v_mfma_f32_16x16x32_bf16 v[88:91], v[136:139], v[206:209], v[88:91]
	v_mfma_f32_16x16x32_bf16 v[76:79], v[128:131], v[214:217], v[76:79]
	v_mfma_f32_16x16x32_bf16 v[72:75], v[136:139], v[214:217], v[72:75]
	v_mfma_f32_16x16x32_bf16 v[124:127], v[132:135], v[190:193], v[124:127]
	v_mfma_f32_16x16x32_bf16 v[120:123], v[140:143], v[190:193], v[120:123]
	v_mfma_f32_16x16x32_bf16 v[108:111], v[132:135], v[202:205], v[108:111]
	v_mfma_f32_16x16x32_bf16 v[104:107], v[140:143], v[202:205], v[104:107]
	v_mfma_f32_16x16x32_bf16 v[92:95], v[132:135], v[210:213], v[92:95]
	v_mfma_f32_16x16x32_bf16 v[88:91], v[140:143], v[210:213], v[88:91]
	v_mfma_f32_16x16x32_bf16 v[76:79], v[132:135], v[218:221], v[76:79]
	v_mfma_f32_16x16x32_bf16 v[72:75], v[140:143], v[218:221], v[72:75]
	s_setprio 0
	s_setprio 1
	v_mfma_f32_16x16x32_bf16 v[116:119], v[144:147], v[186:189], v[116:119]
	v_mfma_f32_16x16x32_bf16 v[112:115], v[168:171], v[186:189], v[112:115]
	v_mfma_f32_16x16x32_bf16 v[100:103], v[144:147], v[194:197], v[100:103]
	v_mfma_f32_16x16x32_bf16 v[96:99], v[168:171], v[194:197], v[96:99]
	v_mfma_f32_16x16x32_bf16 v[84:87], v[144:147], v[206:209], v[84:87]
	v_mfma_f32_16x16x32_bf16 v[80:83], v[168:171], v[206:209], v[80:83]
	v_mfma_f32_16x16x32_bf16 v[68:71], v[144:147], v[214:217], v[68:71]
	v_mfma_f32_16x16x32_bf16 v[64:67], v[168:171], v[214:217], v[64:67]
	v_mfma_f32_16x16x32_bf16 v[116:119], v[148:151], v[190:193], v[116:119]
	v_mfma_f32_16x16x32_bf16 v[112:115], v[172:175], v[190:193], v[112:115]
	v_mfma_f32_16x16x32_bf16 v[100:103], v[148:151], v[202:205], v[100:103]
	v_mfma_f32_16x16x32_bf16 v[96:99], v[172:175], v[202:205], v[96:99]
	v_mfma_f32_16x16x32_bf16 v[84:87], v[148:151], v[210:213], v[84:87]
	v_mfma_f32_16x16x32_bf16 v[80:83], v[172:175], v[210:213], v[80:83]
	v_mfma_f32_16x16x32_bf16 v[68:71], v[148:151], v[218:221], v[68:71]
	v_mfma_f32_16x16x32_bf16 v[64:67], v[172:175], v[218:221], v[64:67]
	s_setprio 0
	s_barrier
	s_add_i32 s42, s57, s9
	v_lshl_add_u64 v[176:177], v[176:177], 0, s[20:21]
	s_mov_b32 m0, s42
	ds_read_b128 v[186:189], v183 offset:49152
	ds_read_b128 v[190:193], v183 offset:50176
	ds_read_b128 v[194:197], v183 offset:51200
	ds_read_b128 v[202:205], v183 offset:52224
	ds_read_b128 v[206:209], v183 offset:53248
	ds_read_b128 v[210:213], v183 offset:54272
	ds_read_b128 v[214:217], v183 offset:55296
	ds_read_b128 v[218:221], v183 offset:56320
	global_load_lds_dwordx4 v[176:177], off
	s_add_i32 m0, s42, 0x2000
	s_add_u32 s40, s40, 0x40080
	v_lshl_add_u64 v[176:177], v[198:199], 0, s[20:21]
	s_addc_u32 s41, s41, 0
	s_add_i32 s42, s58, s9
	global_load_lds_dwordx4 v[176:177], off
	v_lshl_add_u64 v[176:177], s[40:41], 0, v[154:155]
	s_mov_b32 m0, s42
	s_nop 0
	global_load_lds_dwordx4 v[176:177], off
	v_lshl_add_u64 v[176:177], s[40:41], 0, v[158:159]
	s_add_i32 m0, s42, 0x2000
	s_nop 0
	global_load_lds_dwordx4 v[176:177], off
	v_lshl_add_u64 v[176:177], v[222:223], 0, s[20:21]
	s_mov_b32 m0, s51
	s_nop 0
	global_load_lds_dwordx4 v[176:177], off
	v_lshl_add_u64 v[176:177], v[224:225], 0, s[20:21]
	s_mov_b32 m0, s52
	s_nop 0
	global_load_lds_dwordx4 v[176:177], off
	s_waitcnt vmcnt(12)
	s_waitcnt lgkmcnt(0)
	s_barrier
	s_setprio 1
	s_waitcnt lgkmcnt(0)
	v_mfma_f32_16x16x32_bf16 v[60:63], v[128:131], v[186:189], v[60:63]
	v_mfma_f32_16x16x32_bf16 v[56:59], v[136:139], v[186:189], v[56:59]
	v_mfma_f32_16x16x32_bf16 v[44:47], v[128:131], v[194:197], v[44:47]
	v_mfma_f32_16x16x32_bf16 v[40:43], v[136:139], v[194:197], v[40:43]
	v_mfma_f32_16x16x32_bf16 v[28:31], v[128:131], v[206:209], v[28:31]
	v_mfma_f32_16x16x32_bf16 v[24:27], v[136:139], v[206:209], v[24:27]
	v_mfma_f32_16x16x32_bf16 v[12:15], v[128:131], v[214:217], v[12:15]
	v_mfma_f32_16x16x32_bf16 v[8:11], v[136:139], v[214:217], v[8:11]
	v_mfma_f32_16x16x32_bf16 v[60:63], v[132:135], v[190:193], v[60:63]
	v_mfma_f32_16x16x32_bf16 v[56:59], v[140:143], v[190:193], v[56:59]
	v_mfma_f32_16x16x32_bf16 v[44:47], v[132:135], v[202:205], v[44:47]
	v_mfma_f32_16x16x32_bf16 v[40:43], v[140:143], v[202:205], v[40:43]
	v_mfma_f32_16x16x32_bf16 v[28:31], v[132:135], v[210:213], v[28:31]
	v_mfma_f32_16x16x32_bf16 v[24:27], v[140:143], v[210:213], v[24:27]
	v_mfma_f32_16x16x32_bf16 v[12:15], v[132:135], v[218:221], v[12:15]
	v_mfma_f32_16x16x32_bf16 v[8:11], v[140:143], v[218:221], v[8:11]
	s_setprio 0
	s_setprio 1
	v_mfma_f32_16x16x32_bf16 v[52:55], v[144:147], v[186:189], v[52:55]
	v_mfma_f32_16x16x32_bf16 v[48:51], v[168:171], v[186:189], v[48:51]
	v_mfma_f32_16x16x32_bf16 v[36:39], v[144:147], v[194:197], v[36:39]
	v_mfma_f32_16x16x32_bf16 v[32:35], v[168:171], v[194:197], v[32:35]
	v_mfma_f32_16x16x32_bf16 v[20:23], v[144:147], v[206:209], v[20:23]
	v_mfma_f32_16x16x32_bf16 v[16:19], v[168:171], v[206:209], v[16:19]
	v_mfma_f32_16x16x32_bf16 v[4:7], v[144:147], v[214:217], v[4:7]
	v_mfma_f32_16x16x32_bf16 v[0:3], v[168:171], v[214:217], v[0:3]
	v_mfma_f32_16x16x32_bf16 v[52:55], v[148:151], v[190:193], v[52:55]
	v_mfma_f32_16x16x32_bf16 v[48:51], v[172:175], v[190:193], v[48:51]
	v_mfma_f32_16x16x32_bf16 v[36:39], v[148:151], v[202:205], v[36:39]
	v_mfma_f32_16x16x32_bf16 v[32:35], v[172:175], v[202:205], v[32:35]
	v_mfma_f32_16x16x32_bf16 v[20:23], v[148:151], v[210:213], v[20:23]
	v_mfma_f32_16x16x32_bf16 v[16:19], v[172:175], v[210:213], v[16:19]
	v_mfma_f32_16x16x32_bf16 v[4:7], v[148:151], v[218:221], v[4:7]
	v_mfma_f32_16x16x32_bf16 v[0:3], v[172:175], v[218:221], v[0:3]
	s_setprio 0
	s_barrier
	s_add_i32 s56, s56, 2
	s_add_u32 s38, s38, 0x100
	s_addc_u32 s39, s39, 0
	s_add_u32 s29, s29, 0x100
	s_addc_u32 s31, s31, 0
	s_and_b64 vcc, exec, s[22:23]
	s_cbranch_vccz .LBB0_606
	s_barrier
.LBB0_606:
	v_lshl_add_u32 v176, s10, 8, v178
	v_lshl_or_b32 v198, s55, 8, v180
	v_lshlrev_b32_e32 v176, 11, v176
	v_lshl_add_u32 v176, v198, 1, v176
	s_add_u32 s38, s74, 0x10000
	s_addc_u32 s39, s75, 0
	global_load_dwordx4 v[128:131], v176, s[38:39]
	global_load_dwordx4 v[132:135], v176, s[38:39] offset:256
	s_add_u32 s38, s74, 0x18000
	s_addc_u32 s39, s75, 0
	global_load_dwordx4 v[136:139], v176, s[38:39]
	global_load_dwordx4 v[140:143], v176, s[38:39] offset:256
	s_add_u32 s38, s74, 0x40000
	s_addc_u32 s39, s75, 0
	global_load_dwordx4 v[144:147], v176, s[38:39]
	global_load_dwordx4 v[148:151], v176, s[38:39] offset:256
	s_add_u32 s38, s74, 0x48000
	s_addc_u32 s39, s75, 0
	global_load_dwordx4 v[168:171], v176, s[38:39]
	global_load_dwordx4 v[172:175], v176, s[38:39] offset:256
	v_xor_b32_e32 v177, 16, v184
	v_xor_b32_e32 v185, 32, v184
	v_lshlrev_b32_e32 v177, 2, v177
	v_lshlrev_b32_e32 v185, 2, v185
	s_mov_b32 s41, 0xffff0000
	s_waitcnt vmcnt(16)
	v_lshlrev_b32_e32 v186, 16, v228
	v_and_b32_e32 v187, s41, v228
	v_lshlrev_b32_e32 v188, 16, v229
	v_and_b32_e32 v189, s41, v229
	v_lshlrev_b32_e32 v190, 16, v230
	v_and_b32_e32 v191, s41, v230
	v_lshlrev_b32_e32 v192, 16, v231
	v_and_b32_e32 v193, s41, v231
	v_pk_add_f32 v[124:125], v[124:125], v[186:187]
	v_pk_add_f32 v[126:127], v[126:127], v[188:189]
	v_pk_add_f32 v[120:121], v[120:121], v[190:191]
	v_pk_add_f32 v[122:123], v[122:123], v[192:193]
	v_lshlrev_b32_e32 v194, 16, v232
	v_and_b32_e32 v195, s41, v232
	v_lshlrev_b32_e32 v196, 16, v233
	v_and_b32_e32 v197, s41, v233
	v_lshlrev_b32_e32 v202, 16, v234
	v_and_b32_e32 v203, s41, v234
	v_lshlrev_b32_e32 v204, 16, v235
	v_and_b32_e32 v205, s41, v235
	v_pk_add_f32 v[116:117], v[116:117], v[194:195]
	v_pk_add_f32 v[118:119], v[118:119], v[196:197]
	v_pk_add_f32 v[112:113], v[112:113], v[202:203]
	v_pk_add_f32 v[114:115], v[114:115], v[204:205]
	v_pk_mul_f32 v[244:245], v[124:125], v[124:125]
	v_pk_mul_f32 v[246:247], v[126:127], v[126:127]
	v_pk_fma_f32 v[244:245], v[120:121], v[120:121], v[244:245]
	v_pk_fma_f32 v[246:247], v[122:123], v[122:123], v[246:247]
	v_pk_fma_f32 v[244:245], v[116:117], v[116:117], v[244:245]
	v_pk_fma_f32 v[246:247], v[118:119], v[118:119], v[246:247]
	v_pk_fma_f32 v[244:245], v[112:113], v[112:113], v[244:245]
	v_pk_fma_f32 v[246:247], v[114:115], v[114:115], v[246:247]
	v_pk_add_f32 v[244:245], v[244:245], v[246:247]
	s_mov_b32 s40, 0x0
	v_cvt_pk_bf16_f32 v124, v124, v125
	v_cvt_pk_bf16_f32 v125, v126, v127
	v_cvt_pk_bf16_f32 v126, v120, v121
	v_cvt_pk_bf16_f32 v127, v122, v123
	buffer_store_dwordx4 v[124:127], v176, s[12:15], s40 offen sc1
	v_cvt_pk_bf16_f32 v116, v116, v117
	v_cvt_pk_bf16_f32 v117, v118, v119
	v_cvt_pk_bf16_f32 v118, v112, v113
	v_cvt_pk_bf16_f32 v119, v114, v115
	buffer_store_dwordx4 v[116:119], v176, s[12:15], s40 offen offset:256 sc1
	v_add_f32_e32 v252, v244, v245
	v_lshlrev_b32_e32 v186, 16, v236
	v_and_b32_e32 v187, s41, v236
	v_lshlrev_b32_e32 v188, 16, v237
	v_and_b32_e32 v189, s41, v237
	v_lshlrev_b32_e32 v190, 16, v238
	v_and_b32_e32 v191, s41, v238
	v_lshlrev_b32_e32 v192, 16, v239
	v_and_b32_e32 v193, s41, v239
	v_pk_add_f32 v[108:109], v[108:109], v[186:187]
	v_pk_add_f32 v[110:111], v[110:111], v[188:189]
	v_pk_add_f32 v[104:105], v[104:105], v[190:191]
	v_pk_add_f32 v[106:107], v[106:107], v[192:193]
	v_lshlrev_b32_e32 v194, 16, v240
	v_and_b32_e32 v195, s41, v240
	v_lshlrev_b32_e32 v196, 16, v241
	v_and_b32_e32 v197, s41, v241
	v_lshlrev_b32_e32 v202, 16, v242
	v_and_b32_e32 v203, s41, v242
	v_lshlrev_b32_e32 v204, 16, v243
	v_and_b32_e32 v205, s41, v243
	v_pk_add_f32 v[100:101], v[100:101], v[194:195]
	v_pk_add_f32 v[102:103], v[102:103], v[196:197]
	v_pk_add_f32 v[96:97], v[96:97], v[202:203]
	v_pk_add_f32 v[98:99], v[98:99], v[204:205]
	v_pk_mul_f32 v[244:245], v[108:109], v[108:109]
	v_pk_mul_f32 v[246:247], v[110:111], v[110:111]
	v_pk_fma_f32 v[244:245], v[104:105], v[104:105], v[244:245]
	v_pk_fma_f32 v[246:247], v[106:107], v[106:107], v[246:247]
	v_pk_fma_f32 v[244:245], v[100:101], v[100:101], v[244:245]
	v_pk_fma_f32 v[246:247], v[102:103], v[102:103], v[246:247]
	v_pk_fma_f32 v[244:245], v[96:97], v[96:97], v[244:245]
	v_pk_fma_f32 v[246:247], v[98:99], v[98:99], v[246:247]
	v_pk_add_f32 v[244:245], v[244:245], v[246:247]
	s_mov_b32 s40, 0x8000
	v_cvt_pk_bf16_f32 v108, v108, v109
	v_cvt_pk_bf16_f32 v109, v110, v111
	v_cvt_pk_bf16_f32 v110, v104, v105
	v_cvt_pk_bf16_f32 v111, v106, v107
	buffer_store_dwordx4 v[108:111], v176, s[12:15], s40 offen sc1
	v_cvt_pk_bf16_f32 v100, v100, v101
	v_cvt_pk_bf16_f32 v101, v102, v103
	v_cvt_pk_bf16_f32 v102, v96, v97
	v_cvt_pk_bf16_f32 v103, v98, v99
	buffer_store_dwordx4 v[100:103], v176, s[12:15], s40 offen offset:256 sc1
	v_add_f32_e32 v253, v244, v245
	s_waitcnt vmcnt(10)
	v_lshlrev_b32_e32 v186, 16, v128
	v_and_b32_e32 v187, s41, v128
	v_lshlrev_b32_e32 v188, 16, v129
	v_and_b32_e32 v189, s41, v129
	v_lshlrev_b32_e32 v190, 16, v130
	v_and_b32_e32 v191, s41, v130
	v_lshlrev_b32_e32 v192, 16, v131
	v_and_b32_e32 v193, s41, v131
	v_pk_add_f32 v[92:93], v[92:93], v[186:187]
	v_pk_add_f32 v[94:95], v[94:95], v[188:189]
	v_pk_add_f32 v[88:89], v[88:89], v[190:191]
	v_pk_add_f32 v[90:91], v[90:91], v[192:193]
	v_lshlrev_b32_e32 v194, 16, v132
	v_and_b32_e32 v195, s41, v132
	v_lshlrev_b32_e32 v196, 16, v133
	v_and_b32_e32 v197, s41, v133
	v_lshlrev_b32_e32 v202, 16, v134
	v_and_b32_e32 v203, s41, v134
	v_lshlrev_b32_e32 v204, 16, v135
	v_and_b32_e32 v205, s41, v135
	v_pk_add_f32 v[84:85], v[84:85], v[194:195]
	v_pk_add_f32 v[86:87], v[86:87], v[196:197]
	v_pk_add_f32 v[80:81], v[80:81], v[202:203]
	v_pk_add_f32 v[82:83], v[82:83], v[204:205]
	s_add_u32 s38, s74, 0x50000
	s_addc_u32 s39, s75, 0
	global_load_dwordx4 v[128:131], v176, s[38:39]
	global_load_dwordx4 v[132:135], v176, s[38:39] offset:256
	v_pk_mul_f32 v[244:245], v[92:93], v[92:93]
	v_pk_mul_f32 v[246:247], v[94:95], v[94:95]
	v_pk_fma_f32 v[244:245], v[88:89], v[88:89], v[244:245]
	v_pk_fma_f32 v[246:247], v[90:91], v[90:91], v[246:247]
	v_pk_fma_f32 v[244:245], v[84:85], v[84:85], v[244:245]
	v_pk_fma_f32 v[246:247], v[86:87], v[86:87], v[246:247]
	v_pk_fma_f32 v[244:245], v[80:81], v[80:81], v[244:245]
	v_pk_fma_f32 v[246:247], v[82:83], v[82:83], v[246:247]
	v_pk_add_f32 v[244:245], v[244:245], v[246:247]
	s_mov_b32 s40, 0x10000
	v_cvt_pk_bf16_f32 v92, v92, v93
	v_cvt_pk_bf16_f32 v93, v94, v95
	v_cvt_pk_bf16_f32 v94, v88, v89
	v_cvt_pk_bf16_f32 v95, v90, v91
	buffer_store_dwordx4 v[92:95], v176, s[12:15], s40 offen sc1
	v_cvt_pk_bf16_f32 v84, v84, v85
	v_cvt_pk_bf16_f32 v85, v86, v87
	v_cvt_pk_bf16_f32 v86, v80, v81
	v_cvt_pk_bf16_f32 v87, v82, v83
	buffer_store_dwordx4 v[84:87], v176, s[12:15], s40 offen offset:256 sc1
	v_add_f32_e32 v254, v244, v245
	s_waitcnt vmcnt(12)
	v_lshlrev_b32_e32 v186, 16, v136
	v_and_b32_e32 v187, s41, v136
	v_lshlrev_b32_e32 v188, 16, v137
	v_and_b32_e32 v189, s41, v137
	v_lshlrev_b32_e32 v190, 16, v138
	v_and_b32_e32 v191, s41, v138
	v_lshlrev_b32_e32 v192, 16, v139
	v_and_b32_e32 v193, s41, v139
	v_pk_add_f32 v[76:77], v[76:77], v[186:187]
	v_pk_add_f32 v[78:79], v[78:79], v[188:189]
	v_pk_add_f32 v[72:73], v[72:73], v[190:191]
	v_pk_add_f32 v[74:75], v[74:75], v[192:193]
	v_lshlrev_b32_e32 v194, 16, v140
	v_and_b32_e32 v195, s41, v140
	v_lshlrev_b32_e32 v196, 16, v141
	v_and_b32_e32 v197, s41, v141
	v_lshlrev_b32_e32 v202, 16, v142
	v_and_b32_e32 v203, s41, v142
	v_lshlrev_b32_e32 v204, 16, v143
	v_and_b32_e32 v205, s41, v143
	v_pk_add_f32 v[68:69], v[68:69], v[194:195]
	v_pk_add_f32 v[70:71], v[70:71], v[196:197]
	v_pk_add_f32 v[64:65], v[64:65], v[202:203]
	v_pk_add_f32 v[66:67], v[66:67], v[204:205]
	s_add_u32 s38, s74, 0x58000
	s_addc_u32 s39, s75, 0
	global_load_dwordx4 v[136:139], v176, s[38:39]
	global_load_dwordx4 v[140:143], v176, s[38:39] offset:256
	v_pk_mul_f32 v[244:245], v[76:77], v[76:77]
	v_pk_mul_f32 v[246:247], v[78:79], v[78:79]
	v_pk_fma_f32 v[244:245], v[72:73], v[72:73], v[244:245]
	v_pk_fma_f32 v[246:247], v[74:75], v[74:75], v[246:247]
	v_pk_fma_f32 v[244:245], v[68:69], v[68:69], v[244:245]
	v_pk_fma_f32 v[246:247], v[70:71], v[70:71], v[246:247]
	v_pk_fma_f32 v[244:245], v[64:65], v[64:65], v[244:245]
	v_pk_fma_f32 v[246:247], v[66:67], v[66:67], v[246:247]
	v_pk_add_f32 v[244:245], v[244:245], v[246:247]
	s_mov_b32 s40, 0x18000
	v_cvt_pk_bf16_f32 v76, v76, v77
	v_cvt_pk_bf16_f32 v77, v78, v79
	v_cvt_pk_bf16_f32 v78, v72, v73
	v_cvt_pk_bf16_f32 v79, v74, v75
	buffer_store_dwordx4 v[76:79], v176, s[12:15], s40 offen sc1
	v_cvt_pk_bf16_f32 v68, v68, v69
	v_cvt_pk_bf16_f32 v69, v70, v71
	v_cvt_pk_bf16_f32 v70, v64, v65
	v_cvt_pk_bf16_f32 v71, v66, v67
	buffer_store_dwordx4 v[68:71], v176, s[12:15], s40 offen offset:256 sc1
	v_add_f32_e32 v255, v244, v245
	s_waitcnt vmcnt(14)
	v_lshlrev_b32_e32 v186, 16, v144
	v_and_b32_e32 v187, s41, v144
	v_lshlrev_b32_e32 v188, 16, v145
	v_and_b32_e32 v189, s41, v145
	v_lshlrev_b32_e32 v190, 16, v146
	v_and_b32_e32 v191, s41, v146
	v_lshlrev_b32_e32 v192, 16, v147
	v_and_b32_e32 v193, s41, v147
	v_pk_add_f32 v[60:61], v[60:61], v[186:187]
	v_pk_add_f32 v[62:63], v[62:63], v[188:189]
	v_pk_add_f32 v[56:57], v[56:57], v[190:191]
	v_pk_add_f32 v[58:59], v[58:59], v[192:193]
	v_lshlrev_b32_e32 v194, 16, v148
	v_and_b32_e32 v195, s41, v148
	v_lshlrev_b32_e32 v196, 16, v149
	v_and_b32_e32 v197, s41, v149
	v_lshlrev_b32_e32 v202, 16, v150
	v_and_b32_e32 v203, s41, v150
	v_lshlrev_b32_e32 v204, 16, v151
	v_and_b32_e32 v205, s41, v151
	v_pk_add_f32 v[52:53], v[52:53], v[194:195]
	v_pk_add_f32 v[54:55], v[54:55], v[196:197]
	v_pk_add_f32 v[48:49], v[48:49], v[202:203]
	v_pk_add_f32 v[50:51], v[50:51], v[204:205]
	v_pk_mul_f32 v[244:245], v[60:61], v[60:61]
	v_pk_mul_f32 v[246:247], v[62:63], v[62:63]
	v_pk_fma_f32 v[244:245], v[56:57], v[56:57], v[244:245]
	v_pk_fma_f32 v[246:247], v[58:59], v[58:59], v[246:247]
	v_pk_fma_f32 v[244:245], v[52:53], v[52:53], v[244:245]
	v_pk_fma_f32 v[246:247], v[54:55], v[54:55], v[246:247]
	v_pk_fma_f32 v[244:245], v[48:49], v[48:49], v[244:245]
	v_pk_fma_f32 v[246:247], v[50:51], v[50:51], v[246:247]
	v_pk_add_f32 v[244:245], v[244:245], v[246:247]
	s_mov_b32 s40, 0x40000
	v_cvt_pk_bf16_f32 v60, v60, v61
	v_cvt_pk_bf16_f32 v61, v62, v63
	v_cvt_pk_bf16_f32 v62, v56, v57
	v_cvt_pk_bf16_f32 v63, v58, v59
	buffer_store_dwordx4 v[60:63], v176, s[12:15], s40 offen sc1
	v_cvt_pk_bf16_f32 v52, v52, v53
	v_cvt_pk_bf16_f32 v53, v54, v55
	v_cvt_pk_bf16_f32 v54, v48, v49
	v_cvt_pk_bf16_f32 v55, v50, v51
	buffer_store_dwordx4 v[52:55], v176, s[12:15], s40 offen offset:256 sc1
	v_add_f32_e32 v249, v244, v245
	s_waitcnt vmcnt(14)
	v_lshlrev_b32_e32 v186, 16, v168
	v_and_b32_e32 v187, s41, v168
	v_lshlrev_b32_e32 v188, 16, v169
	v_and_b32_e32 v189, s41, v169
	v_lshlrev_b32_e32 v190, 16, v170
	v_and_b32_e32 v191, s41, v170
	v_lshlrev_b32_e32 v192, 16, v171
	v_and_b32_e32 v193, s41, v171
	v_pk_add_f32 v[44:45], v[44:45], v[186:187]
	v_pk_add_f32 v[46:47], v[46:47], v[188:189]
	v_pk_add_f32 v[40:41], v[40:41], v[190:191]
	v_pk_add_f32 v[42:43], v[42:43], v[192:193]
	v_lshlrev_b32_e32 v194, 16, v172
	v_and_b32_e32 v195, s41, v172
	v_lshlrev_b32_e32 v196, 16, v173
	v_and_b32_e32 v197, s41, v173
	v_lshlrev_b32_e32 v202, 16, v174
	v_and_b32_e32 v203, s41, v174
	v_lshlrev_b32_e32 v204, 16, v175
	v_and_b32_e32 v205, s41, v175
	v_pk_add_f32 v[36:37], v[36:37], v[194:195]
	v_pk_add_f32 v[38:39], v[38:39], v[196:197]
	v_pk_add_f32 v[32:33], v[32:33], v[202:203]
	v_pk_add_f32 v[34:35], v[34:35], v[204:205]
	v_pk_mul_f32 v[244:245], v[44:45], v[44:45]
	v_pk_mul_f32 v[246:247], v[46:47], v[46:47]
	v_pk_fma_f32 v[244:245], v[40:41], v[40:41], v[244:245]
	v_pk_fma_f32 v[246:247], v[42:43], v[42:43], v[246:247]
	v_pk_fma_f32 v[244:245], v[36:37], v[36:37], v[244:245]
	v_pk_fma_f32 v[246:247], v[38:39], v[38:39], v[246:247]
	v_pk_fma_f32 v[244:245], v[32:33], v[32:33], v[244:245]
	v_pk_fma_f32 v[246:247], v[34:35], v[34:35], v[246:247]
	v_pk_add_f32 v[244:245], v[244:245], v[246:247]
	s_mov_b32 s40, 0x48000
	v_cvt_pk_bf16_f32 v44, v44, v45
	v_cvt_pk_bf16_f32 v45, v46, v47
	v_cvt_pk_bf16_f32 v46, v40, v41
	v_cvt_pk_bf16_f32 v47, v42, v43
	buffer_store_dwordx4 v[44:47], v176, s[12:15], s40 offen sc1
	v_cvt_pk_bf16_f32 v36, v36, v37
	v_cvt_pk_bf16_f32 v37, v38, v39
	v_cvt_pk_bf16_f32 v38, v32, v33
	v_cvt_pk_bf16_f32 v39, v34, v35
	buffer_store_dwordx4 v[36:39], v176, s[12:15], s40 offen offset:256 sc1
	v_add_f32_e32 v250, v244, v245
	s_waitcnt vmcnt(10)
	v_lshlrev_b32_e32 v186, 16, v128
	v_and_b32_e32 v187, s41, v128
	v_lshlrev_b32_e32 v188, 16, v129
	v_and_b32_e32 v189, s41, v129
	v_lshlrev_b32_e32 v190, 16, v130
	v_and_b32_e32 v191, s41, v130
	v_lshlrev_b32_e32 v192, 16, v131
	v_and_b32_e32 v193, s41, v131
	v_pk_add_f32 v[28:29], v[28:29], v[186:187]
	v_pk_add_f32 v[30:31], v[30:31], v[188:189]
	v_pk_add_f32 v[24:25], v[24:25], v[190:191]
	v_pk_add_f32 v[26:27], v[26:27], v[192:193]
	v_lshlrev_b32_e32 v194, 16, v132
	v_and_b32_e32 v195, s41, v132
	v_lshlrev_b32_e32 v196, 16, v133
	v_and_b32_e32 v197, s41, v133
	v_lshlrev_b32_e32 v202, 16, v134
	v_and_b32_e32 v203, s41, v134
	v_lshlrev_b32_e32 v204, 16, v135
	v_and_b32_e32 v205, s41, v135
	v_pk_add_f32 v[20:21], v[20:21], v[194:195]
	v_pk_add_f32 v[22:23], v[22:23], v[196:197]
	v_pk_add_f32 v[16:17], v[16:17], v[202:203]
	v_pk_add_f32 v[18:19], v[18:19], v[204:205]
	v_pk_mul_f32 v[244:245], v[28:29], v[28:29]
	v_pk_mul_f32 v[246:247], v[30:31], v[30:31]
	v_pk_fma_f32 v[244:245], v[24:25], v[24:25], v[244:245]
	v_pk_fma_f32 v[246:247], v[26:27], v[26:27], v[246:247]
	v_pk_fma_f32 v[244:245], v[20:21], v[20:21], v[244:245]
	v_pk_fma_f32 v[246:247], v[22:23], v[22:23], v[246:247]
	v_pk_fma_f32 v[244:245], v[16:17], v[16:17], v[244:245]
	v_pk_fma_f32 v[246:247], v[18:19], v[18:19], v[246:247]
	v_pk_add_f32 v[244:245], v[244:245], v[246:247]
	s_mov_b32 s40, 0x50000
	v_cvt_pk_bf16_f32 v28, v28, v29
	v_cvt_pk_bf16_f32 v29, v30, v31
	v_cvt_pk_bf16_f32 v30, v24, v25
	v_cvt_pk_bf16_f32 v31, v26, v27
	v_cvt_pk_bf16_f32 v20, v20, v21
	v_cvt_pk_bf16_f32 v21, v22, v23
	v_cvt_pk_bf16_f32 v22, v16, v17
	v_cvt_pk_bf16_f32 v23, v18, v19
	v_add_f32_e32 v251, v244, v245
	s_waitcnt vmcnt(6)
	v_lshlrev_b32_e32 v186, 16, v136
	v_and_b32_e32 v187, s41, v136
	v_lshlrev_b32_e32 v188, 16, v137
	v_and_b32_e32 v189, s41, v137
	v_lshlrev_b32_e32 v190, 16, v138
	v_and_b32_e32 v191, s41, v138
	v_lshlrev_b32_e32 v192, 16, v139
	v_and_b32_e32 v193, s41, v139
	v_pk_add_f32 v[12:13], v[12:13], v[186:187]
	v_pk_add_f32 v[14:15], v[14:15], v[188:189]
	v_pk_add_f32 v[8:9], v[8:9], v[190:191]
	v_pk_add_f32 v[10:11], v[10:11], v[192:193]
	v_lshlrev_b32_e32 v194, 16, v140
	v_and_b32_e32 v195, s41, v140
	v_lshlrev_b32_e32 v196, 16, v141
	v_and_b32_e32 v197, s41, v141
	v_lshlrev_b32_e32 v202, 16, v142
	v_and_b32_e32 v203, s41, v142
	v_lshlrev_b32_e32 v204, 16, v143
	v_and_b32_e32 v205, s41, v143
	v_pk_add_f32 v[4:5], v[4:5], v[194:195]
	v_pk_add_f32 v[6:7], v[6:7], v[196:197]
	v_pk_add_f32 v[0:1], v[0:1], v[202:203]
	v_pk_add_f32 v[2:3], v[2:3], v[204:205]
	v_pk_mul_f32 v[244:245], v[12:13], v[12:13]
	v_pk_mul_f32 v[246:247], v[14:15], v[14:15]
	v_pk_fma_f32 v[244:245], v[8:9], v[8:9], v[244:245]
	v_pk_fma_f32 v[246:247], v[10:11], v[10:11], v[246:247]
	v_pk_fma_f32 v[244:245], v[4:5], v[4:5], v[244:245]
	v_pk_fma_f32 v[246:247], v[6:7], v[6:7], v[246:247]
	v_pk_fma_f32 v[244:245], v[0:1], v[0:1], v[244:245]
	v_pk_fma_f32 v[246:247], v[2:3], v[2:3], v[246:247]
	v_pk_add_f32 v[244:245], v[244:245], v[246:247]
	s_mov_b32 s40, 0x58000
	v_cvt_pk_bf16_f32 v12, v12, v13
	v_cvt_pk_bf16_f32 v13, v14, v15
	v_cvt_pk_bf16_f32 v14, v8, v9
	v_cvt_pk_bf16_f32 v15, v10, v11
	v_cvt_pk_bf16_f32 v4, v4, v5
	v_cvt_pk_bf16_f32 v5, v6, v7
	v_cvt_pk_bf16_f32 v6, v0, v1
	v_cvt_pk_bf16_f32 v7, v2, v3
	v_add_f32_e32 v201, v244, v245
	ds_bpermute_b32 v128, v177, v252
	ds_bpermute_b32 v129, v177, v253
	ds_bpermute_b32 v130, v177, v254
	ds_bpermute_b32 v131, v177, v255
	ds_bpermute_b32 v132, v177, v249
	ds_bpermute_b32 v133, v177, v250
	ds_bpermute_b32 v134, v177, v251
	ds_bpermute_b32 v135, v177, v201
	s_waitcnt lgkmcnt(7)
	v_add_f32_e32 v252, v252, v128
	s_waitcnt lgkmcnt(6)
	v_add_f32_e32 v253, v253, v129
	s_waitcnt lgkmcnt(5)
	v_add_f32_e32 v254, v254, v130
	s_waitcnt lgkmcnt(4)
	v_add_f32_e32 v255, v255, v131
	s_waitcnt lgkmcnt(3)
	v_add_f32_e32 v249, v249, v132
	s_waitcnt lgkmcnt(2)
	v_add_f32_e32 v250, v250, v133
	s_waitcnt lgkmcnt(1)
	v_add_f32_e32 v251, v251, v134
	s_waitcnt lgkmcnt(0)
	v_add_f32_e32 v201, v201, v135
	ds_bpermute_b32 v128, v185, v252
	ds_bpermute_b32 v129, v185, v253
	ds_bpermute_b32 v130, v185, v254
	ds_bpermute_b32 v131, v185, v255
	ds_bpermute_b32 v132, v185, v249
	ds_bpermute_b32 v133, v185, v250
	ds_bpermute_b32 v134, v185, v251
	ds_bpermute_b32 v135, v185, v201
	s_waitcnt lgkmcnt(7)
	v_add_f32_e32 v252, v252, v128
	s_waitcnt lgkmcnt(6)
	v_add_f32_e32 v253, v253, v129
	s_waitcnt lgkmcnt(5)
	v_add_f32_e32 v254, v254, v130
	s_waitcnt lgkmcnt(4)
	v_add_f32_e32 v255, v255, v131
	s_waitcnt lgkmcnt(3)
	v_add_f32_e32 v249, v249, v132
	s_waitcnt lgkmcnt(2)
	v_add_f32_e32 v250, v250, v133
	s_waitcnt lgkmcnt(1)
	v_add_f32_e32 v251, v251, v134
	s_waitcnt lgkmcnt(0)
	v_add_f32_e32 v201, v201, v135
	v_lshrrev_b32_e32 v198, 4, v184
	v_cmp_eq_u32_e64 s[38:39], 1, v198
	v_cmp_eq_u32_e64 s[40:41], 2, v198
	v_cmp_eq_u32_e32 vcc, 3, v198
	v_lshl_add_u32 v136, s10, 8, v178
	v_lshl_add_u32 v136, v198, 4, v136
	v_cndmask_b32_e64 v128, v252, v253, s[38:39]
	v_cndmask_b32_e64 v128, v128, v254, s[40:41]
	v_cndmask_b32_e32 v128, v128, v255, vcc
	v_cndmask_b32_e64 v129, v249, v250, s[38:39]
	v_cndmask_b32_e64 v129, v129, v251, s[40:41]
	v_cndmask_b32_e32 v129, v129, v201, vcc
	s_lshl_b32 s38, s55, 4
	s_lshl_b32 s39, s50, 2
	s_add_i32 s38, s38, s39
	v_lshl_add_u32 v136, v136, 6, s38
	global_store_dword v136, v128, s[2:3]
	v_add_u32_e32 v137, 0x2000, v136
	global_store_dword v137, v129, s[2:3]
	s_mov_b32 s40, 0x50000
	buffer_store_dwordx4 v[28:31], v176, s[12:15], s40 offen sc1
	s_mov_b32 s40, 0x50000
	buffer_store_dwordx4 v[20:23], v176, s[12:15], s40 offen offset:256 sc1
	s_mov_b32 s40, 0x58000
	buffer_store_dwordx4 v[12:15], v176, s[12:15], s40 offen sc1
	s_mov_b32 s40, 0x58000
	buffer_store_dwordx4 v[4:7], v176, s[12:15], s40 offen offset:256 sc1
	s_andn2_b64 vcc, exec, s[4:5]
	s_mov_b64 s[4:5], -1
	s_cbranch_vccnz .LBB0_595
	s_andn2_b64 vcc, exec, s[18:19]
	s_cbranch_vccnz .LBB0_594
	s_barrier
	s_branch .LBB0_594
